# P4: residual x tile preloaded into GEMM accumulators during the P3->P4 grid barrier wait (acc=x then acc+=A.B); epilogue x loads and zero-init removed
# baseline (speedup 1.0000x reference)
.LBB0_624:
	s_or_b64 exec, exec, s[4:5]
	s_cmp_gt_i32 s2, 63
	s_cbranch_scc0 .Lxp_skip_a
	v_readlane_b32 s5, v239, 49
	v_readlane_b32 s6, v239, 50
	s_lshl_b32 s8, s5, 5
	v_readlane_b32 s7, v239, 51
	s_mul_i32 s5, s5, 33
	s_and_b64 s[6:7], s[6:7], exec
	s_cselect_b32 s8, s5, s8
	v_readlane_b32 s5, v239, 52
	s_add_i32 s8, s8, s5
	s_ashr_i32 s5, s8, 31
	s_lshr_b32 s5, s5, 26
	s_add_i32 s5, s8, s5
	s_ashr_i32 s6, s5, 6
	s_and_b32 s5, s5, 0xffc0
	s_sub_i32 s5, s8, s5
	s_bfe_i32 s8, s5, 0x80000
	s_bfe_u32 s8, s8, 0x3000c
	s_add_i32 s7, s5, s8
	s_bfe_i32 s8, s7, 0x80000
	s_and_b32 s7, s7, 0xf8
	s_sub_i32 s5, s5, s7
	s_lshl_b32 s6, s6, 3
	s_sext_i32_i16 s8, s8
	s_sext_i32_i8 s5, s5
	s_lshr_b32 s8, s8, 3
	s_add_i32 s6, s6, s5
	s_sext_i32_i8 s8, s8
	s_lshr_b32 s9, s97, 6
	s_lshr_b32 s10, s9, 2
	s_and_b32 s9, s9, 3
	s_lshl_b32 s6, s6, 8
	s_lshl_b32 s10, s10, 6
	s_add_i32 s6, s6, s10
	s_lshl_b32 s8, s8, 8
	s_lshl_b32 s9, s9, 5
	s_add_i32 s8, s8, s9
	v_mbcnt_lo_u32_b32 v226, -1, 0
	v_mbcnt_hi_u32_b32 v226, -1, v226
	v_and_b32_e32 v227, 15, v226
	v_add_u32_e32 v227, s6, v227
	v_lshrrev_b32_e32 v226, 2, v226
	v_and_b32_e32 v226, 12, v226
	v_add_u32_e32 v226, s8, v226
	v_lshlrev_b32_e32 v226, 2, v226
	v_lshl_add_u32 v226, v227, 13, v226
	v_mov_b32_e32 v227, 0
	v_lshl_add_u64 v[226:227], s[44:45], 0, v[226:227]
	global_load_dwordx4 v[124:127], v[226:227], off nt
	global_load_dwordx4 v[120:123], v[226:227], off offset:64 nt
	global_load_dwordx4 v[116:119], v[226:227], off offset:512 nt
	global_load_dwordx4 v[112:115], v[226:227], off offset:576 nt
	s_mov_b64 s[12:13], 0x20000
	v_lshl_add_u64 v[230:231], v[226:227], 0, s[12:13]
	global_load_dwordx4 v[108:111], v[230:231], off nt
	global_load_dwordx4 v[104:107], v[230:231], off offset:64 nt
	global_load_dwordx4 v[100:103], v[230:231], off offset:512 nt
	global_load_dwordx4 v[96:99], v[230:231], off offset:576 nt
	s_mov_b64 s[12:13], 0x40000
	v_lshl_add_u64 v[228:229], v[226:227], 0, s[12:13]
	global_load_dwordx4 v[92:95], v[228:229], off nt
	global_load_dwordx4 v[88:91], v[228:229], off offset:64 nt
	global_load_dwordx4 v[84:87], v[228:229], off offset:512 nt
	global_load_dwordx4 v[80:83], v[228:229], off offset:576 nt
	s_mov_b64 s[12:13], 0x60000
	v_lshl_add_u64 v[230:231], v[226:227], 0, s[12:13]
	global_load_dwordx4 v[76:79], v[230:231], off nt
	global_load_dwordx4 v[72:75], v[230:231], off offset:64 nt
	global_load_dwordx4 v[68:71], v[230:231], off offset:512 nt
	global_load_dwordx4 v[64:67], v[230:231], off offset:576 nt
	s_mov_b64 s[12:13], 0x100000
	v_lshl_add_u64 v[228:229], v[226:227], 0, s[12:13]
	global_load_dwordx4 v[60:63], v[228:229], off nt
	global_load_dwordx4 v[56:59], v[228:229], off offset:64 nt
	global_load_dwordx4 v[52:55], v[228:229], off offset:512 nt
	global_load_dwordx4 v[48:51], v[228:229], off offset:576 nt
	s_mov_b64 s[12:13], 0x120000
	v_lshl_add_u64 v[230:231], v[226:227], 0, s[12:13]
	global_load_dwordx4 v[44:47], v[230:231], off nt
	global_load_dwordx4 v[40:43], v[230:231], off offset:64 nt
	global_load_dwordx4 v[36:39], v[230:231], off offset:512 nt
	global_load_dwordx4 v[32:35], v[230:231], off offset:576 nt
	s_mov_b64 s[12:13], 0x140000
	v_lshl_add_u64 v[228:229], v[226:227], 0, s[12:13]
	global_load_dwordx4 v[28:31], v[228:229], off nt
	global_load_dwordx4 v[24:27], v[228:229], off offset:64 nt
	global_load_dwordx4 v[20:23], v[228:229], off offset:512 nt
	global_load_dwordx4 v[16:19], v[228:229], off offset:576 nt
	s_mov_b64 s[12:13], 0x160000
	v_lshl_add_u64 v[230:231], v[226:227], 0, s[12:13]
	global_load_dwordx4 v[12:15], v[230:231], off nt
	global_load_dwordx4 v[8:11], v[230:231], off offset:64 nt
	global_load_dwordx4 v[4:7], v[230:231], off offset:512 nt
	global_load_dwordx4 v[0:3], v[230:231], off offset:576 nt

.LBB0_648:
	v_mbcnt_lo_u32_b32 v240, -1, 0
	v_mbcnt_hi_u32_b32 v240, -1, v240
	s_cmpk_gt_i32 s2, 0xff
	v_add_u32_e32 v144, s97, v240
	s_nop 0
	v_readfirstlane_b32 s28, v144
	s_cbranch_scc1 .LBB0_700
	s_cmp_gt_i32 s2, 63
	s_cbranch_scc1 .Lxp_skip_b
	v_readlane_b32 s5, v239, 49
	v_readlane_b32 s6, v239, 50
	s_lshl_b32 s8, s5, 5
	v_readlane_b32 s7, v239, 51
	s_mul_i32 s5, s5, 33
	s_and_b64 s[6:7], s[6:7], exec
	s_cselect_b32 s8, s5, s8
	v_readlane_b32 s5, v239, 52
	s_add_i32 s8, s8, s5
	s_ashr_i32 s5, s8, 31
	s_lshr_b32 s5, s5, 26
	s_add_i32 s5, s8, s5
	s_ashr_i32 s6, s5, 6
	s_and_b32 s5, s5, 0xffc0
	s_sub_i32 s5, s8, s5
	s_bfe_i32 s8, s5, 0x80000
	s_bfe_u32 s8, s8, 0x3000c
	s_add_i32 s7, s5, s8
	s_bfe_i32 s8, s7, 0x80000
	s_and_b32 s7, s7, 0xf8
	s_sub_i32 s5, s5, s7
	s_lshl_b32 s6, s6, 3
	s_sext_i32_i16 s8, s8
	s_sext_i32_i8 s5, s5
	s_lshr_b32 s8, s8, 3
	s_add_i32 s6, s6, s5
	s_sext_i32_i8 s8, s8
	s_lshr_b32 s9, s97, 6
	s_lshr_b32 s10, s9, 2
	s_and_b32 s9, s9, 3
	s_lshl_b32 s6, s6, 8
	s_lshl_b32 s10, s10, 6
	s_add_i32 s6, s6, s10
	s_lshl_b32 s8, s8, 8
	s_lshl_b32 s9, s9, 5
	s_add_i32 s8, s8, s9
	v_mbcnt_lo_u32_b32 v226, -1, 0
	v_mbcnt_hi_u32_b32 v226, -1, v226
	v_and_b32_e32 v227, 15, v226
	v_add_u32_e32 v227, s6, v227
	v_lshrrev_b32_e32 v226, 2, v226
	v_and_b32_e32 v226, 12, v226
	v_add_u32_e32 v226, s8, v226
	v_lshlrev_b32_e32 v226, 2, v226
	v_lshl_add_u32 v226, v227, 13, v226
	v_mov_b32_e32 v227, 0
	v_lshl_add_u64 v[226:227], s[44:45], 0, v[226:227]
	global_load_dwordx4 v[124:127], v[226:227], off nt
	global_load_dwordx4 v[120:123], v[226:227], off offset:64 nt
	global_load_dwordx4 v[116:119], v[226:227], off offset:512 nt
	global_load_dwordx4 v[112:115], v[226:227], off offset:576 nt
	s_mov_b64 s[12:13], 0x20000
	v_lshl_add_u64 v[230:231], v[226:227], 0, s[12:13]
	global_load_dwordx4 v[108:111], v[230:231], off nt
	global_load_dwordx4 v[104:107], v[230:231], off offset:64 nt
	global_load_dwordx4 v[100:103], v[230:231], off offset:512 nt
	global_load_dwordx4 v[96:99], v[230:231], off offset:576 nt
	s_mov_b64 s[12:13], 0x40000
	v_lshl_add_u64 v[228:229], v[226:227], 0, s[12:13]
	global_load_dwordx4 v[92:95], v[228:229], off nt
	global_load_dwordx4 v[88:91], v[228:229], off offset:64 nt
	global_load_dwordx4 v[84:87], v[228:229], off offset:512 nt
	global_load_dwordx4 v[80:83], v[228:229], off offset:576 nt
	s_mov_b64 s[12:13], 0x60000
	v_lshl_add_u64 v[230:231], v[226:227], 0, s[12:13]
	global_load_dwordx4 v[76:79], v[230:231], off nt
	global_load_dwordx4 v[72:75], v[230:231], off offset:64 nt
	global_load_dwordx4 v[68:71], v[230:231], off offset:512 nt
	global_load_dwordx4 v[64:67], v[230:231], off offset:576 nt
	s_mov_b64 s[12:13], 0x100000
	v_lshl_add_u64 v[228:229], v[226:227], 0, s[12:13]
	global_load_dwordx4 v[60:63], v[228:229], off nt
	global_load_dwordx4 v[56:59], v[228:229], off offset:64 nt
	global_load_dwordx4 v[52:55], v[228:229], off offset:512 nt
	global_load_dwordx4 v[48:51], v[228:229], off offset:576 nt
	s_mov_b64 s[12:13], 0x120000
	v_lshl_add_u64 v[230:231], v[226:227], 0, s[12:13]
	global_load_dwordx4 v[44:47], v[230:231], off nt
	global_load_dwordx4 v[40:43], v[230:231], off offset:64 nt
	global_load_dwordx4 v[36:39], v[230:231], off offset:512 nt
	global_load_dwordx4 v[32:35], v[230:231], off offset:576 nt
	s_mov_b64 s[12:13], 0x140000
	v_lshl_add_u64 v[228:229], v[226:227], 0, s[12:13]
	global_load_dwordx4 v[28:31], v[228:229], off nt
	global_load_dwordx4 v[24:27], v[228:229], off offset:64 nt
	global_load_dwordx4 v[20:23], v[228:229], off offset:512 nt
	global_load_dwordx4 v[16:19], v[228:229], off offset:576 nt
	s_mov_b64 s[12:13], 0x160000
	v_lshl_add_u64 v[230:231], v[226:227], 0, s[12:13]
	global_load_dwordx4 v[12:15], v[230:231], off nt
	global_load_dwordx4 v[8:11], v[230:231], off offset:64 nt
	global_load_dwordx4 v[4:7], v[230:231], off offset:512 nt
	global_load_dwordx4 v[0:3], v[230:231], off offset:576 nt
.Lxp_skip_b:
	v_lshlrev_b32_e32 v240, 4, v144
	v_add_u32_e32 v241, 0x2000, v240
	v_ashrrev_i32_e32 v242, 31, v241
	v_lshrrev_b32_e32 v242, 22, v242
	v_add_u32_e32 v242, v241, v242
	v_ashrrev_i32_e32 v248, 10, v242
	v_mul_i32_i24_e32 v243, 0x400, v248
	v_sub_u32_e32 v241, v241, v243
	v_lshrrev_b32_e32 v243, 4, v241
	v_bitop3_b32 v241, v243, v241, 32 bitop3:0x6c
	v_ashrrev_i32_e32 v243, 31, v241
	v_lshrrev_b32_e32 v243, 26, v243
	v_add_u32_e32 v243, v241, v243
	v_ashrrev_i32_e32 v249, 6, v243
	v_and_b32_e32 v243, 0xc0, v243
	v_sub_u32_e32 v241, v241, v243
	v_mov_b32_e32 v243, 1
	v_lshlrev_b32_e32 v242, 5, v248
	v_ashrrev_i16_sdwa v241, v243, sext(v241) dst_sel:DWORD dst_unused:UNUSED_PAD src0_sel:DWORD src1_sel:BYTE_0
	s_ashr_i32 s4, s28, 6
	v_readlane_b32 s5, v239, 49
	v_and_b32_e32 v242, 32, v242
	v_bfe_i32 v250, v241, 0, 16
	v_readlane_b32 s6, v239, 50
	s_ashr_i32 s1, s28, 8
	s_lshl_b32 s9, s4, 10
	s_lshl_b32 s0, s5, 5
	v_add_u32_e32 v241, v242, v250
	v_lshlrev_b32_e32 v242, 3, v248
	v_readlane_b32 s7, v239, 51
	s_mul_i32 s5, s5, 33
	v_and_b32_e32 v242, 0xffff0, v242
	s_and_b64 s[6:7], s[6:7], exec
	v_add_lshl_u32 v242, v249, v242, 12
	s_cselect_b32 s0, s5, s0
	v_readlane_b32 s5, v239, 52
	v_lshl_add_u32 v128, v241, 1, v242
	v_bfe_i32 v242, v144, 27, 1
	s_add_i32 s0, s0, s5
	v_lshrrev_b32_e32 v242, 22, v242
	s_ashr_i32 s5, s0, 31
	v_add_u32_e32 v242, v240, v242
	s_lshr_b32 s5, s5, 26
	v_and_b32_e32 v242, 0xfffffc00, v242
	s_add_i32 s5, s0, s5
	v_sub_u32_e32 v240, v240, v242
	s_ashr_i32 s6, s5, 6
	s_and_b32 s5, s5, 0xffc0
	v_lshrrev_b32_e32 v242, 4, v240
	s_sub_i32 s5, s0, s5
	v_bitop3_b32 v240, v242, v240, 32 bitop3:0x6c
	s_bfe_i32 s0, s5, 0x80000
	v_ashrrev_i32_e32 v242, 31, v240
	s_bfe_u32 s0, s0, 0x3000c
	v_ashrrev_i32_e32 v241, 31, v144
	v_lshrrev_b32_e32 v242, 26, v242
	s_add_i32 s7, s5, s0
	v_lshrrev_b32_e32 v241, 26, v241
	v_add_u32_e32 v242, v240, v242
	s_bfe_i32 s0, s7, 0x80000
	s_and_b32 s7, s7, 0xf8
	v_add_u32_e32 v241, v144, v241
	v_ashrrev_i32_e32 v252, 6, v242
	v_and_b32_e32 v242, 0xc0, v242
	s_sub_i32 s5, s5, s7
	v_ashrrev_i32_e32 v251, 6, v241
	v_sub_u32_e32 v240, v240, v242
	s_lshl_b32 s6, s6, 3
	s_sext_i32_i16 s0, s0
	s_sext_i32_i8 s5, s5
	v_lshlrev_b32_e32 v241, 5, v251
	v_ashrrev_i16_sdwa v240, v243, sext(v240) dst_sel:DWORD dst_unused:UNUSED_PAD src0_sel:DWORD src1_sel:BYTE_0
	s_lshr_b32 s0, s0, 3
	s_add_i32 s6, s6, s5
	v_and_b32_e32 v241, 32, v241
	v_bfe_i32 v253, v240, 0, 16
	s_ashr_i32 s7, s6, 31
	s_bfe_i64 s[12:13], s[0:1], 0x100000
	v_add_u32_e32 v240, v241, v253
	v_lshlrev_b32_e32 v241, 3, v251
	s_lshl_b64 s[10:11], s[6:7], 20
	s_lshl_b64 s[12:13], s[12:13], 20
	v_and_b32_e32 v241, 0xffff0, v241
	s_add_u32 s22, s34, s12
	v_add_lshl_u32 v241, v252, v241, 12
	s_addc_u32 s23, s35, s13
	s_add_i32 s29, s9, 0
	v_lshl_add_u32 v130, v240, 1, v241
	s_add_i32 m0, s29, 0x10000
	v_mov_b32_e32 v131, 0
	global_load_lds_dwordx4 v130, s[22:23]
	s_add_i32 m0, s29, 0x12000
	s_add_u32 s12, s22, 0x80000
	global_load_lds_dwordx4 v128, s[22:23]
	s_addc_u32 s13, s23, 0
	s_add_i32 m0, s29, 0x14000
	v_mov_b32_e32 v129, v131
	global_load_lds_dwordx4 v130, s[12:13]
	s_add_i32 m0, s29, 0x16000
	s_add_u32 s10, s30, s10
	s_addc_u32 s11, s31, s11
	s_add_i32 s33, s29, 0x2000
	global_load_lds_dwordx4 v128, s[12:13]
	s_mov_b32 m0, s29
	s_add_u32 s12, s10, 0x80000
	global_load_lds_dwordx4 v130, s[10:11]
	s_mov_b32 m0, s33
	s_addc_u32 s13, s11, 0
	s_add_i32 s36, s29, 0x4000
	global_load_lds_dwordx4 v128, s[10:11]
	s_mov_b32 m0, s36
	s_add_i32 s37, s29, 0x6000
	global_load_lds_dwordx4 v130, s[12:13]
	s_mov_b32 m0, s37
	v_lshl_add_u64 v[246:247], s[22:23], 0, v[130:131]
	global_load_lds_dwordx4 v128, s[12:13]
	v_lshl_add_u64 v[244:245], s[22:23], 0, v[128:129]
	v_lshl_add_u64 v[242:243], s[10:11], 0, v[130:131]
	s_cmp_lg_u32 s1, 1
	v_lshl_add_u64 v[240:241], s[10:11], 0, v[128:129]
	s_cbranch_scc1 .LBB0_651
	s_barrier
.LBB0_651:
	s_mov_b64 s[12:13], 0x80
	s_and_b32 s7, s4, 3
	s_add_i32 m0, s29, 0x18000
	v_lshl_add_u64 v[246:247], v[246:247], 0, s[12:13]
	s_lshl_b32 s38, s1, 6
	s_lshl_b32 s1, s1, 13
	s_lshl_b32 s14, s7, 12
	s_waitcnt vmcnt(2)
	s_barrier
	global_load_lds_dwordx4 v[246:247], off
	v_lshl_add_u64 v[244:245], v[244:245], 0, s[12:13]
	s_add_i32 m0, s29, 0x1a000
	s_add_i32 s39, s29, 0x8000
	s_add_i32 s40, s29, 0xa000
	global_load_lds_dwordx4 v[244:245], off
	v_lshl_add_u64 v[242:243], v[242:243], 0, s[12:13]
	s_mov_b32 m0, s39
	s_add_u32 s4, s22, 0x80080
	global_load_lds_dwordx4 v[242:243], off
	v_lshl_add_u64 v[240:241], v[240:241], 0, s[12:13]
	s_mov_b32 m0, s40
	s_addc_u32 s5, s23, 0
	global_load_lds_dwordx4 v[240:241], off
	s_add_i32 m0, s29, 0x1c000
	v_lshl_add_u64 v[240:241], s[4:5], 0, v[130:131]
	global_load_lds_dwordx4 v[240:241], off
	v_lshl_add_u64 v[240:241], s[4:5], 0, v[128:129]
	s_add_i32 m0, s29, 0x1e000
	v_and_b32_e32 v145, 15, v144
	global_load_lds_dwordx4 v[240:241], off
	v_and_b32_e32 v240, 48, v144
	v_lshlrev_b32_e32 v241, 2, v144
	v_lshl_or_b32 v240, v145, 6, v240
	v_and_b32_e32 v241, 32, v241
	v_bitop3_b32 v244, v240, s1, v241 bitop3:0xde
	v_bitop3_b32 v147, v240, s14, v241 bitop3:0xde
	v_lshlrev_b32_e32 v240, 15, v251
	v_and_b32_e32 v240, 0xffff0000, v240
	v_lshl_add_u32 v240, v252, 12, v240
	v_and_b32_e32 v241, 1, v251
	v_lshl_or_b32 v240, v241, 6, v240
	s_sext_i32_i8 s8, s0
	s_mov_b64 s[0:1], 0x80080
	v_lshl_add_u32 v240, v253, 1, v240
	v_mov_b32_e32 v241, v131
	v_lshl_add_u64 v[132:133], v[240:241], 0, s[0:1]
	v_lshlrev_b32_e32 v240, 15, v248
	v_and_b32_e32 v240, 0xffff0000, v240
	v_lshl_add_u32 v240, v249, 12, v240
	v_and_b32_e32 v241, 1, v248
	v_lshl_or_b32 v240, v241, 6, v240
	s_waitcnt vmcnt(6)
	v_lshl_add_u32 v240, v250, 1, v240
	v_mov_b32_e32 v241, v131
	v_lshl_add_u64 v[134:135], v[240:241], 0, s[0:1]
	v_add_u32_e32 v148, 0, v244
	v_or_b32_e32 v146, s38, v145
	s_mov_b32 s41, 0
	v_mov_b64_e32 v[136:137], 0x100
	v_mov_b64_e32 v[138:139], 0xff
	s_add_i32 s42, 0, 0x10000
	s_add_i32 s43, 0, 0x14000
	s_barrier
	s_branch .LBB0_654

.LBB0_666:
	s_lshl_b32 s10, s6, 8
	s_add_i32 s1, s10, s38
	s_lshl_b32 s0, s7, 5
	v_or_b32_e32 v130, s1, v145
	s_lshl_b32 s1, s8, 8
	s_or_b32 s0, s1, s0
	v_lshrrev_b32_e32 v128, 2, v144
	v_ashrrev_i32_e32 v131, 31, v130
	v_and_or_b32 v128, v128, 12, s0
	v_lshlrev_b64 v[132:133], 13, v[130:131]
	v_ashrrev_i32_e32 v129, 31, v128
	v_lshl_add_u64 v[132:133], s[44:45], 0, v[132:133]
	v_lshl_add_u64 v[148:149], v[128:129], 2, v[132:133]
	s_barrier
	v_mbcnt_hi_u32_b32 v148, -1, v169
	v_and_b32_e32 v145, 64, v148
	v_and_b32_e32 v147, 63, v144
	v_xor_b32_e32 v144, 16, v148
	v_add_u32_e32 v154, 64, v145
	v_cmp_lt_i32_e32 vcc, v144, v154
	s_lshl_b32 s2, s7, 2
	s_add_i32 s4, s2, 0
	v_cndmask_b32_e32 v144, v148, v144, vcc
	v_lshlrev_b32_e32 v149, 2, v144
	v_cmp_gt_u32_e64 s[0:1], 16, v147
	v_pk_mul_f32 v[132:133], v[126:127], v[126:127]
	v_pk_mul_f32 v[134:135], v[124:125], v[124:125]
	v_pk_mul_f32 v[136:137], v[122:123], v[122:123]
	v_pk_mul_f32 v[138:139], v[120:121], v[120:121]
	v_pk_mul_f32 v[140:141], v[118:119], v[118:119]
	v_pk_mul_f32 v[142:143], v[116:117], v[116:117]
	v_add_f32_e32 v136, v136, v137
	v_add_f32_e32 v137, v138, v139
	v_add_f32_e32 v132, v132, v133
	v_add_f32_e32 v133, v134, v135
	v_pk_mul_f32 v[144:145], v[114:115], v[114:115]
	v_pk_mul_f32 v[150:151], v[112:113], v[112:113]
	v_add_f32_e32 v134, v140, v141
	v_add_f32_e32 v135, v142, v143
	v_add_f32_e32 v136, v137, v136
	v_add_f32_e32 v132, v133, v132
	v_add_f32_e32 v138, v144, v145
	v_add_f32_e32 v139, v150, v151
	v_add_f32_e32 v133, v135, v134
	v_add_f32_e32 v132, v132, v136
	v_add_f32_e32 v132, v132, v133
	v_add_f32_e32 v133, v139, v138
	v_add_f32_e32 v132, v132, v133
	ds_bpermute_b32 v133, v149, v132
	v_xor_b32_e32 v134, 32, v148
	v_cmp_lt_i32_e32 vcc, v134, v154
	v_lshl_add_u32 v150, v146, 4, s4
	s_waitcnt lgkmcnt(0)
	v_add_f32_e32 v132, v132, v133
	v_cndmask_b32_e32 v134, v148, v134, vcc
	v_lshlrev_b32_e32 v151, 2, v134
	ds_bpermute_b32 v133, v151, v132
	s_and_saveexec_b64 s[2:3], s[0:1]
	s_cbranch_execz .LBB0_668
	s_waitcnt lgkmcnt(0)
	v_add_f32_e32 v132, v132, v133
	ds_write_b32 v150, v132
.LBB0_668:
	s_or_b64 exec, exec, s[2:3]
	v_or_b32_e32 v132, 16, v130
	s_waitcnt lgkmcnt(0)
	v_ashrrev_i32_e32 v133, 31, v132
	v_lshlrev_b64 v[132:133], 13, v[132:133]
	v_lshl_add_u64 v[132:133], s[44:45], 0, v[132:133]
	v_lshl_add_u64 v[144:145], v[128:129], 2, v[132:133]
	v_pk_mul_f32 v[132:133], v[110:111], v[110:111]
	v_pk_mul_f32 v[134:135], v[108:109], v[108:109]
	v_pk_mul_f32 v[136:137], v[106:107], v[106:107]
	v_pk_mul_f32 v[138:139], v[104:105], v[104:105]
	v_pk_mul_f32 v[140:141], v[102:103], v[102:103]
	v_pk_mul_f32 v[142:143], v[100:101], v[100:101]
	v_add_f32_e32 v136, v136, v137
	v_add_f32_e32 v137, v138, v139
	v_add_f32_e32 v132, v132, v133
	v_add_f32_e32 v133, v134, v135
	v_pk_mul_f32 v[144:145], v[98:99], v[98:99]
	v_pk_mul_f32 v[152:153], v[96:97], v[96:97]
	v_add_f32_e32 v134, v140, v141
	v_add_f32_e32 v135, v142, v143
	v_add_f32_e32 v136, v137, v136
	v_add_f32_e32 v132, v133, v132
	v_add_f32_e32 v138, v144, v145
	v_add_f32_e32 v139, v152, v153
	v_add_f32_e32 v133, v135, v134
	v_add_f32_e32 v132, v132, v136
	v_add_f32_e32 v132, v132, v133
	v_add_f32_e32 v133, v139, v138
	v_add_f32_e32 v132, v132, v133
	ds_bpermute_b32 v133, v149, v132
	s_waitcnt lgkmcnt(0)
	v_add_f32_e32 v132, v132, v133
	ds_bpermute_b32 v133, v151, v132
	s_and_saveexec_b64 s[2:3], s[0:1]
	s_cbranch_execz .LBB0_670
	s_waitcnt lgkmcnt(0)
	v_add_f32_e32 v132, v132, v133
	ds_write_b32 v150, v132 offset:256
.LBB0_670:
	s_or_b64 exec, exec, s[2:3]
	v_or_b32_e32 v132, 32, v130
	s_waitcnt lgkmcnt(0)
	v_ashrrev_i32_e32 v133, 31, v132
	v_lshlrev_b64 v[132:133], 13, v[132:133]
	v_lshl_add_u64 v[132:133], s[44:45], 0, v[132:133]
	v_lshl_add_u64 v[144:145], v[128:129], 2, v[132:133]
	v_pk_mul_f32 v[132:133], v[94:95], v[94:95]
	v_pk_mul_f32 v[134:135], v[92:93], v[92:93]
	v_pk_mul_f32 v[136:137], v[90:91], v[90:91]
	v_pk_mul_f32 v[138:139], v[88:89], v[88:89]
	v_pk_mul_f32 v[140:141], v[86:87], v[86:87]
	v_pk_mul_f32 v[142:143], v[84:85], v[84:85]
	v_add_f32_e32 v136, v136, v137
	v_add_f32_e32 v137, v138, v139
	v_add_f32_e32 v132, v132, v133
	v_add_f32_e32 v133, v134, v135
	v_pk_mul_f32 v[144:145], v[82:83], v[82:83]
	v_pk_mul_f32 v[152:153], v[80:81], v[80:81]
	v_add_f32_e32 v134, v140, v141
	v_add_f32_e32 v135, v142, v143
	v_add_f32_e32 v136, v137, v136
	v_add_f32_e32 v132, v133, v132
	v_add_f32_e32 v138, v144, v145
	v_add_f32_e32 v139, v152, v153
	v_add_f32_e32 v133, v135, v134
	v_add_f32_e32 v132, v132, v136
	v_add_f32_e32 v132, v132, v133
	v_add_f32_e32 v133, v139, v138
	v_add_f32_e32 v132, v132, v133
	ds_bpermute_b32 v133, v149, v132
	s_waitcnt lgkmcnt(0)
	v_add_f32_e32 v132, v132, v133
	ds_bpermute_b32 v133, v151, v132
	s_and_saveexec_b64 s[2:3], s[0:1]
	s_cbranch_execz .LBB0_672
	s_waitcnt lgkmcnt(0)
	v_add_f32_e32 v132, v132, v133
	ds_write_b32 v150, v132 offset:512
.LBB0_672:
	s_or_b64 exec, exec, s[2:3]
	v_or_b32_e32 v132, 48, v130
	s_waitcnt lgkmcnt(0)
	v_ashrrev_i32_e32 v133, 31, v132
	v_lshlrev_b64 v[132:133], 13, v[132:133]
	v_lshl_add_u64 v[132:133], s[44:45], 0, v[132:133]
	v_lshl_add_u64 v[144:145], v[128:129], 2, v[132:133]
	v_pk_mul_f32 v[132:133], v[78:79], v[78:79]
	v_pk_mul_f32 v[134:135], v[76:77], v[76:77]
	v_pk_mul_f32 v[136:137], v[74:75], v[74:75]
	v_pk_mul_f32 v[138:139], v[72:73], v[72:73]
	v_pk_mul_f32 v[140:141], v[70:71], v[70:71]
	v_pk_mul_f32 v[142:143], v[68:69], v[68:69]
	v_add_f32_e32 v136, v136, v137
	v_add_f32_e32 v137, v138, v139
	v_add_f32_e32 v132, v132, v133
	v_add_f32_e32 v133, v134, v135
	v_pk_mul_f32 v[144:145], v[66:67], v[66:67]
	v_pk_mul_f32 v[152:153], v[64:65], v[64:65]
	v_add_f32_e32 v134, v140, v141
	v_add_f32_e32 v135, v142, v143
	v_add_f32_e32 v136, v137, v136
	v_add_f32_e32 v132, v133, v132
	v_add_f32_e32 v138, v144, v145
	v_add_f32_e32 v139, v152, v153
	v_add_f32_e32 v133, v135, v134
	v_add_f32_e32 v132, v132, v136
	v_add_f32_e32 v132, v132, v133
	v_add_f32_e32 v133, v139, v138
	v_add_f32_e32 v132, v132, v133
	ds_bpermute_b32 v133, v149, v132
	s_waitcnt lgkmcnt(0)
	v_add_f32_e32 v132, v132, v133
	ds_bpermute_b32 v133, v151, v132
	s_and_saveexec_b64 s[2:3], s[0:1]
	s_cbranch_execz .LBB0_674
	s_waitcnt lgkmcnt(0)
	v_add_f32_e32 v132, v132, v133
	ds_write_b32 v150, v132 offset:768
.LBB0_674:
	s_or_b64 exec, exec, s[2:3]
	s_waitcnt lgkmcnt(0)
	v_lshlrev_b64 v[132:133], 13, v[130:131]
	v_lshl_add_u64 v[132:133], s[44:45], 0, v[132:133]
	v_lshl_add_u64 v[132:133], v[128:129], 2, v[132:133]
	s_mov_b64 s[2:3], 0x100000
	v_lshl_add_u64 v[152:153], v[132:133], 0, s[2:3]
	v_add_co_u32_e32 v142, vcc, 0x100000, v132
	v_addc_co_u32_e32 v143, vcc, 0, v133, vcc
	s_nop 0
	v_add_u32_e32 v148, 0x80, v146
	v_pk_mul_f32 v[134:135], v[58:59], v[58:59]
	v_pk_mul_f32 v[136:137], v[56:57], v[56:57]
	v_pk_mul_f32 v[138:139], v[54:55], v[54:55]
	v_pk_mul_f32 v[142:143], v[62:63], v[62:63]
	v_pk_mul_f32 v[144:145], v[60:61], v[60:61]
	v_pk_mul_f32 v[140:141], v[52:53], v[52:53]
	v_add_f32_e32 v134, v134, v135
	v_add_f32_e32 v135, v136, v137
	v_add_f32_e32 v136, v138, v139
	v_add_f32_e32 v138, v142, v143
	v_add_f32_e32 v139, v144, v145
	v_pk_mul_f32 v[152:153], v[50:51], v[50:51]
	v_pk_mul_f32 v[154:155], v[48:49], v[48:49]
	v_add_f32_e32 v137, v140, v141
	v_add_f32_e32 v134, v135, v134
	v_add_f32_e32 v138, v139, v138
	v_add_f32_e32 v135, v137, v136
	v_add_f32_e32 v136, v152, v153
	v_add_f32_e32 v137, v154, v155
	v_add_f32_e32 v134, v138, v134
	v_add_f32_e32 v134, v134, v135
	v_add_f32_e32 v135, v137, v136
	v_add_f32_e32 v134, v134, v135
	ds_bpermute_b32 v135, v149, v134
	s_waitcnt lgkmcnt(0)
	v_add_f32_e32 v134, v134, v135
	ds_bpermute_b32 v135, v151, v134
	s_and_saveexec_b64 s[2:3], s[0:1]
	s_cbranch_execz .LBB0_676
	v_lshl_add_u32 v136, v148, 4, s4
	s_waitcnt lgkmcnt(0)
	v_add_f32_e32 v134, v134, v135
	ds_write_b32 v136, v134
.LBB0_676:
	s_or_b64 exec, exec, s[2:3]
	v_add_co_u32_e32 v134, vcc, 0x120000, v132
	s_mov_b64 s[2:3], 0x120000
	s_waitcnt lgkmcnt(0)
	v_addc_co_u32_e32 v135, vcc, 0, v133, vcc
	v_lshl_add_u64 v[132:133], v[132:133], 0, s[2:3]
	v_pk_mul_f32 v[132:133], v[46:47], v[46:47]
	v_pk_mul_f32 v[134:135], v[44:45], v[44:45]
	v_pk_mul_f32 v[136:137], v[42:43], v[42:43]
	v_pk_mul_f32 v[138:139], v[40:41], v[40:41]
	v_pk_mul_f32 v[140:141], v[38:39], v[38:39]
	v_pk_mul_f32 v[142:143], v[36:37], v[36:37]
	v_add_f32_e32 v132, v132, v133
	v_add_f32_e32 v133, v134, v135
	v_add_f32_e32 v134, v136, v137
	v_add_f32_e32 v135, v138, v139
	v_pk_mul_f32 v[144:145], v[34:35], v[34:35]
	v_pk_mul_f32 v[152:153], v[32:33], v[32:33]
	v_add_f32_e32 v136, v140, v141
	v_add_f32_e32 v137, v142, v143
	v_add_f32_e32 v132, v133, v132
	v_add_f32_e32 v133, v135, v134
	v_add_f32_e32 v138, v144, v145
	v_add_f32_e32 v139, v152, v153
	v_add_f32_e32 v134, v137, v136
	v_add_f32_e32 v132, v132, v133
	v_add_f32_e32 v132, v132, v134
	v_add_f32_e32 v133, v139, v138
	v_add_f32_e32 v132, v132, v133
	ds_bpermute_b32 v133, v149, v132
	s_waitcnt lgkmcnt(0)
	v_add_f32_e32 v132, v132, v133
	ds_bpermute_b32 v133, v151, v132
	s_and_saveexec_b64 s[2:3], s[0:1]
	s_cbranch_execz .LBB0_678
	s_waitcnt lgkmcnt(0)
	v_add_f32_e32 v132, v132, v133
	ds_write_b32 v150, v132 offset:2304
.LBB0_678:
	s_or_b64 exec, exec, s[2:3]
	v_lshlrev_b64 v[130:131], 13, v[130:131]
	v_lshl_add_u64 v[130:131], s[44:45], 0, v[130:131]
	v_lshl_add_u64 v[130:131], v[128:129], 2, v[130:131]
	s_mov_b64 s[2:3], 0x140000
	v_lshl_add_u64 v[144:145], v[130:131], 0, s[2:3]
	v_add_co_u32_e32 v140, vcc, 0x140000, v130
	s_waitcnt lgkmcnt(0)
	v_addc_co_u32_e32 v141, vcc, 0, v131, vcc
	s_nop 0
	v_pk_mul_f32 v[132:133], v[26:27], v[26:27]
	v_pk_mul_f32 v[134:135], v[24:25], v[24:25]
	v_pk_mul_f32 v[136:137], v[22:23], v[22:23]
	v_pk_mul_f32 v[140:141], v[30:31], v[30:31]
	v_pk_mul_f32 v[142:143], v[28:29], v[28:29]
	v_pk_mul_f32 v[138:139], v[20:21], v[20:21]
	v_add_f32_e32 v132, v132, v133
	v_add_f32_e32 v133, v134, v135
	v_add_f32_e32 v134, v136, v137
	v_add_f32_e32 v136, v140, v141
	v_add_f32_e32 v137, v142, v143
	v_pk_mul_f32 v[144:145], v[18:19], v[18:19]
	v_pk_mul_f32 v[152:153], v[16:17], v[16:17]
	v_add_f32_e32 v135, v138, v139
	v_add_f32_e32 v132, v133, v132
	v_add_f32_e32 v136, v137, v136
	v_add_f32_e32 v133, v135, v134
	v_add_f32_e32 v134, v144, v145
	v_add_f32_e32 v135, v152, v153
	v_add_f32_e32 v132, v136, v132
	v_add_f32_e32 v132, v132, v133
	v_add_f32_e32 v133, v135, v134
	v_add_f32_e32 v132, v132, v133
	ds_bpermute_b32 v133, v149, v132
	s_waitcnt lgkmcnt(0)
	v_add_f32_e32 v132, v132, v133
	ds_bpermute_b32 v133, v151, v132
	s_and_saveexec_b64 s[2:3], s[0:1]
	s_cbranch_execz .LBB0_680
	s_waitcnt lgkmcnt(0)
	v_add_f32_e32 v132, v132, v133
	ds_write_b32 v150, v132 offset:2560
.LBB0_680:
	s_or_b64 exec, exec, s[2:3]
	v_add_co_u32_e32 v132, vcc, 0x160000, v130
	s_mov_b64 s[2:3], 0x160000
	s_waitcnt lgkmcnt(0)
	v_addc_co_u32_e32 v133, vcc, 0, v131, vcc
	v_lshl_add_u64 v[130:131], v[130:131], 0, s[2:3]
	v_mov_b64_e32 v[138:139], v[10:11]
	v_mov_b64_e32 v[142:143], v[14:15]
	v_mov_b64_e32 v[144:145], v[12:13]
	v_mov_b64_e32 v[140:141], v[8:9]
	v_mov_b64_e32 v[134:135], v[6:7]
	v_mov_b64_e32 v[136:137], v[4:5]
	v_mov_b64_e32 v[130:131], v[2:3]
	v_mov_b64_e32 v[132:133], v[0:1]
	v_pk_mul_f32 v[0:1], v[142:143], v[142:143]
	v_pk_mul_f32 v[2:3], v[144:145], v[144:145]
	v_pk_mul_f32 v[4:5], v[138:139], v[138:139]
	v_pk_mul_f32 v[6:7], v[140:141], v[140:141]
	v_pk_mul_f32 v[8:9], v[134:135], v[134:135]
	v_pk_mul_f32 v[10:11], v[136:137], v[136:137]
	v_add_f32_e32 v0, v0, v1
	v_add_f32_e32 v1, v2, v3
	v_add_f32_e32 v2, v4, v5
	v_add_f32_e32 v3, v6, v7
	v_pk_mul_f32 v[12:13], v[130:131], v[130:131]
	v_pk_mul_f32 v[14:15], v[132:133], v[132:133]
	v_add_f32_e32 v4, v8, v9
	v_add_f32_e32 v5, v10, v11
	v_add_f32_e32 v0, v1, v0
	v_add_f32_e32 v1, v3, v2
	v_add_f32_e32 v6, v12, v13
	v_add_f32_e32 v7, v14, v15
	v_add_f32_e32 v2, v5, v4
	v_add_f32_e32 v0, v0, v1
	v_add_f32_e32 v0, v0, v2
	v_add_f32_e32 v1, v7, v6
	v_add_f32_e32 v0, v0, v1
	ds_bpermute_b32 v1, v149, v0
	s_waitcnt lgkmcnt(0)
	v_add_f32_e32 v0, v0, v1
	ds_bpermute_b32 v1, v151, v0
	s_and_saveexec_b64 s[2:3], s[0:1]
	s_cbranch_execz .LBB0_682
	s_waitcnt lgkmcnt(0)
	v_add_f32_e32 v0, v0, v1
	ds_write_b32 v150, v0 offset:2816
